# v46 + norm1 phase: nt only on the streaming x loads, per-batch adaLN parameter loads back to the default cache policy
# speedup vs baseline: 1.0194x; 1.0075x over previous
; __global__ void __launch_bounds__(NWAVES * 64, 2) fwd_kernel(Args args_unused) {
;     ...
;         { const int nrow = grouped ? (4 * SEQ + 4 * CTXL) : MT;
;           for (int r = gw; r < nrow; r += NGW) { const int mrow = (!grouped || r < 4 * SEQ) ? r : ML + (r - 4 * SEQ); P1_ROW(mrow); } }
.LBB0_173:
	v_lshl_add_u64 v[30:31], s[20:21], 0, v[4:5]
	global_load_dwordx4 v[14:17], v[30:31], off nt
	global_load_dwordx4 v[18:21], v[30:31], off offset:1024 nt
	global_load_dwordx4 v[22:25], v[30:31], off offset:3072 nt
	global_load_dwordx4 v[26:29], v[30:31], off offset:2048 nt
	s_min_i32 s8, s16, 0x8000
	s_ashr_i32 s8, s8, 12
	s_mul_hi_i32 s21, s8, 0x6000
	s_mulk_i32 s8, 0x6000
	s_add_u32 s20, s12, s8
	s_addc_u32 s21, s13, s21
	v_lshl_add_u64 v[54:55], s[20:21], 0, v[4:5]
	v_add_co_u32_e32 v30, vcc, s3, v54
	v_lshl_add_u64 v[56:57], v[54:55], 0, s[14:15]
	s_nop 0
	v_addc_co_u32_e32 v31, vcc, 0, v55, vcc
	global_load_dwordx4 v[30:33], v[30:31], off nt
	s_nop 0
	global_load_dwordx4 v[34:37], v[56:57], off offset:1024
	global_load_dwordx4 v[38:41], v[2:3], off offset:1024
	global_load_dwordx4 v[42:45], v[2:3], off
	global_load_dwordx4 v[46:49], v[54:55], off offset:1024
	global_load_dwordx4 v[50:53], v[54:55], off
	s_lshl_b64 s[16:17], s[16:17], 11
	s_add_i32 s23, s23, s24
	s_cmp_ge_i32 s23, s0
	s_waitcnt vmcnt(9)
	v_pk_mul_f32 v[58:59], v[16:17], v[16:17]
	v_pk_mul_f32 v[60:61], v[14:15], v[14:15]
	s_waitcnt vmcnt(8)
	v_pk_mul_f32 v[62:63], v[20:21], v[20:21]
	v_pk_mul_f32 v[64:65], v[18:19], v[18:19]
	v_pk_mov_b32 v[70:71], v[60:61], v[58:59] op_sel:[1,0]
	v_mov_b32_e32 v61, v59
	v_pk_mov_b32 v[58:59], v[64:65], v[62:63] op_sel:[1,0]
	v_mov_b32_e32 v65, v63
	s_waitcnt vmcnt(7)
	v_mul_f32_e32 v69, v23, v23
	s_waitcnt vmcnt(6)
	v_mul_f32_e32 v66, v27, v27
	v_mul_f32_e32 v68, v29, v29
	v_pk_add_f32 v[60:61], v[70:71], v[60:61]
	v_pk_add_f32 v[58:59], v[58:59], v[64:65]
	v_mul_f32_e32 v13, v22, v22
	v_mul_f32_e32 v72, v24, v24
	v_mul_f32_e32 v73, v25, v25
	v_pk_fma_f32 v[62:63], v[26:27], v[26:27], v[66:67] op_sel_hi:[1,1,0]
	v_pk_fma_f32 v[66:67], v[28:29], v[28:29], v[68:69] op_sel_hi:[1,1,0]
	v_pk_add_f32 v[60:61], v[60:61], v[60:61] op_sel:[0,1] op_sel_hi:[1,0]
	v_pk_add_f32 v[58:59], v[58:59], v[58:59] op_sel:[0,1] op_sel_hi:[1,0]
	v_mov_b32_e32 v63, v72
	v_mov_b32_e32 v67, v73
	v_mov_b32_e32 v61, v13
	v_mov_b32_e32 v59, v69
	v_pk_add_f32 v[62:63], v[62:63], v[66:67]
	v_pk_add_f32 v[58:59], v[60:61], v[58:59]
	s_waitcnt vmcnt(5)
	v_pk_add_f32 v[32:33], v[32:33], 1.0 op_sel_hi:[1,0]
	v_pk_add_f32 v[58:59], v[58:59], v[62:63]
	v_pk_add_f32 v[30:31], v[30:31], 1.0 op_sel_hi:[1,0]
	v_add_f32_e32 v13, v58, v59
	ds_bpermute_b32 v58, v6, v13
	s_waitcnt vmcnt(4)
	v_pk_add_f32 v[36:37], v[36:37], 1.0 op_sel_hi:[1,0]
	v_pk_add_f32 v[34:35], v[34:35], 1.0 op_sel_hi:[1,0]
	s_waitcnt lgkmcnt(0)
	v_add_f32_e32 v13, v13, v58
	ds_bpermute_b32 v58, v7, v13
	s_waitcnt lgkmcnt(0)
	v_add_f32_e32 v13, v13, v58
	ds_bpermute_b32 v58, v8, v13
	s_waitcnt lgkmcnt(0)
	v_add_f32_e32 v13, v13, v58
	ds_bpermute_b32 v58, v9, v13
	s_waitcnt lgkmcnt(0)
	v_add_f32_e32 v13, v13, v58
	ds_bpermute_b32 v58, v10, v13
	s_waitcnt lgkmcnt(0)
	v_add_f32_e32 v13, v13, v58
	ds_bpermute_b32 v60, v11, v13
	v_lshl_add_u64 v[58:59], v[0:1], 0, s[16:17]
	s_waitcnt lgkmcnt(0)
	v_add_f32_e32 v13, v13, v60
	v_fmamk_f32 v13, v13, 0x3a800000, v12
	v_mul_f32_e32 v60, 0x4b800000, v13
	v_cmp_gt_f32_e32 vcc, s1, v13
	s_nop 1
	v_cndmask_b32_e32 v13, v13, v60, vcc
	v_rsq_f32_e32 v13, v13
	s_nop 0
	v_mul_f32_e32 v60, 0x45800000, v13
	v_cndmask_b32_e32 v60, v13, v60, vcc
	v_pk_mul_f32 v[16:17], v[60:61], v[16:17] op_sel_hi:[0,1]
	v_pk_mul_f32 v[14:15], v[60:61], v[14:15] op_sel_hi:[0,1]
	v_pk_mul_f32 v[20:21], v[60:61], v[20:21] op_sel_hi:[0,1]
	v_pk_mul_f32 v[18:19], v[60:61], v[18:19] op_sel_hi:[0,1]
	s_waitcnt vmcnt(2)
	v_pk_mul_f32 v[14:15], v[42:43], v[14:15]
	v_pk_mul_f32 v[16:17], v[44:45], v[16:17]
	v_pk_mul_f32 v[18:19], v[38:39], v[18:19]
	v_pk_mul_f32 v[20:21], v[40:41], v[20:21]
	s_waitcnt vmcnt(0)
	v_pk_fma_f32 v[16:17], v[32:33], v[16:17], v[52:53]
	v_pk_fma_f32 v[14:15], v[30:31], v[14:15], v[50:51]
	v_pk_fma_f32 v[20:21], v[36:37], v[20:21], v[48:49]
	v_pk_fma_f32 v[18:19], v[34:35], v[18:19], v[46:47]
	v_cvt_pk_bf16_f32 v14, v14, v15
	v_cvt_pk_bf16_f32 v15, v16, v17
	v_cvt_pk_bf16_f32 v16, v18, v19
	v_cvt_pk_bf16_f32 v17, v20, v21
	global_store_dwordx2 v[58:59], v[14:15], off sc1
	global_store_dwordx2 v[58:59], v[16:17], off offset:512 sc1
	global_load_dwordx4 v[14:17], v[56:57], off offset:2048
	s_nop 0
	global_load_dwordx4 v[18:21], v[2:3], off offset:2048
	global_load_dwordx4 v[30:33], v[56:57], off offset:3072
	global_load_dwordx4 v[34:37], v[2:3], off offset:3072
	global_load_dwordx4 v[38:41], v[54:55], off offset:2048
	global_load_dwordx4 v[42:45], v[54:55], off offset:3072
	v_pk_mul_f32 v[28:29], v[60:61], v[28:29] op_sel_hi:[0,1]
	v_pk_mul_f32 v[26:27], v[60:61], v[26:27] op_sel_hi:[0,1]
	v_pk_mul_f32 v[24:25], v[60:61], v[24:25] op_sel_hi:[0,1]
	v_pk_mul_f32 v[22:23], v[60:61], v[22:23] op_sel_hi:[0,1]
	s_waitcnt vmcnt(5)
	v_pk_add_f32 v[16:17], v[16:17], 1.0 op_sel_hi:[1,0]
	v_pk_add_f32 v[14:15], v[14:15], 1.0 op_sel_hi:[1,0]
	s_waitcnt vmcnt(4)
	v_pk_mul_f32 v[18:19], v[18:19], v[26:27]
	v_pk_mul_f32 v[20:21], v[20:21], v[28:29]
	s_waitcnt vmcnt(3)
	v_pk_add_f32 v[26:27], v[32:33], 1.0 op_sel_hi:[1,0]
	v_pk_add_f32 v[28:29], v[30:31], 1.0 op_sel_hi:[1,0]
	s_waitcnt vmcnt(2)
	v_pk_mul_f32 v[22:23], v[34:35], v[22:23]
	v_pk_mul_f32 v[24:25], v[36:37], v[24:25]
	s_waitcnt vmcnt(1)
	v_pk_fma_f32 v[16:17], v[16:17], v[20:21], v[40:41]
	v_pk_fma_f32 v[14:15], v[14:15], v[18:19], v[38:39]
	s_waitcnt vmcnt(0)
	v_pk_fma_f32 v[18:19], v[26:27], v[24:25], v[44:45]
	v_pk_fma_f32 v[20:21], v[28:29], v[22:23], v[42:43]
	v_cvt_pk_bf16_f32 v14, v14, v15
	v_cvt_pk_bf16_f32 v15, v16, v17
	v_cvt_pk_bf16_f32 v16, v20, v21
	v_cvt_pk_bf16_f32 v17, v18, v19
	global_store_dwordx2 v[58:59], v[14:15], off offset:1024 sc1
	global_store_dwordx2 v[58:59], v[16:17], off offset:1536 sc1
	s_cbranch_scc1 .LBB0_178
